# inline-constant 0 as srcC on the 12 remaining chain-opening QK MFMAs of the attention prologue/tail (zero-tile reads removed), on top of v91
# speedup vs baseline: 1.0016x; 1.0016x over previous
.LBB0_728:
	s_ashr_i32 s24, s56, 31
	s_lshr_b32 s25, s24, 26
	s_add_i32 s25, s56, s25
	s_ashr_i32 s28, s25, 6
	s_and_b32 s25, s25, 0xffffc0
	s_sub_i32 s40, s56, s25
	s_lshr_b32 s24, s24, 23
	s_lshr_b32 s25, s28, 29
	s_add_i32 s24, s56, s24
	s_add_i32 s25, s28, s25
	s_ashr_i32 s24, s24, 9
	s_and_b32 s25, s25, -8
	v_mov_b32_e32 v90, v201
	s_sub_i32 s44, s28, s25
	s_ashr_i32 s25, s24, 31
	v_readfirstlane_b32 s60, v90
	s_lshl_b32 s40, s40, 8
	s_ashr_i32 s57, s60, 6
	s_lshl_b64 s[28:29], s[24:25], 14
	s_ashr_i32 s41, s40, 31
	s_add_u32 s28, s28, s40
	s_addc_u32 s29, s29, s41
	s_lshl_b32 s40, s57, 5
	s_ashr_i32 s41, s40, 31
	s_add_u32 s42, s28, s40
	s_addc_u32 s43, s29, s41
	s_lshl_b64 s[28:29], s[42:43], 10
	s_add_u32 s45, s3, s28
	s_addc_u32 s46, s26, s29
	s_lshl_b32 s28, s44, 6
	s_ashr_i32 s29, s28, 31
	s_lshl_b64 s[40:41], s[28:29], 1
	s_add_u32 s62, s45, s40
	s_addc_u32 s63, s46, s41
	s_lshl_b64 s[24:25], s[24:25], 22
	s_add_u32 s45, s48, s24
	s_addc_u32 s46, s49, s25
	s_lshl_b32 s28, s44, 4
	s_andn2_b32 s28, s28, 63
	s_ashr_i32 s29, s28, 31
	s_lshl_b64 s[28:29], s[28:29], 1
	s_add_u32 s44, s45, s28
	s_addc_u32 s45, s46, s29
	s_add_u32 s46, s50, s24
	s_addc_u32 s47, s51, s25
	v_and_b32_e32 v186, 63, v90
	s_add_u32 s58, s46, s28
	s_addc_u32 s59, s47, s29
	v_lshlrev_b32_e32 v88, 8, v186
	v_mov_b32_e32 v89, v2
	s_lshl_b32 s46, s57, 3
	v_lshl_add_u64 v[0:1], s[44:45], 0, v[88:89]
	s_ashr_i32 s47, s46, 31
	s_lshl_b32 s44, s57, 4
	v_bfe_u32 v91, v90, 2, 4
	v_lshl_add_u64 v[182:183], s[46:47], 1, v[0:1]
	v_and_or_b32 v0, s44, 48, v91
	s_ashr_i32 s44, s60, 3
	v_lshlrev_b32_e32 v0, 8, v0
	v_mov_b32_e32 v1, v2
	s_andn2_b32 s44, s44, 31
	v_lshl_add_u64 v[0:1], s[58:59], 0, v[0:1]
	s_ashr_i32 s45, s44, 31
	s_lshl_b32 s59, s57, 10
	v_lshlrev_b32_e32 v187, 3, v90
	s_cmp_lg_u32 0, -1
	v_and_b32_e32 v193, 24, v187
	s_cselect_b32 s58, 0, 0
	v_lshl_add_u64 v[0:1], s[44:45], 1, v[0:1]
	v_lshlrev_b32_e32 v4, 1, v193
	v_mov_b32_e32 v5, v2
	s_add_i32 s59, s59, s58
	s_mov_b32 s61, m0
	s_mov_b32 m0, s59
	s_nop 0
	global_load_lds_dwordx4 v[182:183], off
	s_mov_b32 m0, s61
	v_and_b32_e32 v188, 31, v90
	v_lshl_add_u64 v[180:181], v[0:1], 0, v[4:5]
	s_add_i32 s58, s59, 0x6000
	s_mov_b32 s61, m0
	s_mov_b32 m0, s58
	s_nop 0
	global_load_lds_dwordx4 v[180:181], off
	s_mov_b32 m0, s61
	v_lshl_add_u64 v[0:1], v[182:183], 0, s[34:35]
	v_bfe_u32 v189, v90, 5, 1
	s_add_i32 s61, s59, 0x2000
	s_mov_b32 s64, m0
	s_mov_b32 m0, s61
	s_nop 0
	global_load_lds_dwordx4 v[0:1], off
	s_mov_b32 m0, s64
	v_lshlrev_b32_e32 v0, 10, v188
	v_lshl_or_b32 v0, v189, 4, v0
	global_load_dwordx4 v[160:163], v0, s[62:63]
	global_load_dwordx4 v[156:159], v0, s[62:63] offset:32
	global_load_dwordx4 v[144:147], v0, s[62:63] offset:64
	global_load_dwordx4 v[136:139], v0, s[62:63] offset:96
	v_lshlrev_b32_e32 v1, 10, v189
	v_lshlrev_b32_e32 v3, 4, v188
	v_mov_b32_e32 v14, v2
	v_mov_b32_e32 v15, v2
	v_add3_u32 v191, 0, v1, v3
	v_mov_b32_e32 v0, v2
	v_mov_b32_e32 v1, v2
	v_mov_b32_e32 v3, v2
	v_mov_b32_e32 v4, v2
	v_mov_b32_e32 v6, v2
	v_mov_b32_e32 v7, v2
	v_mov_b32_e32 v8, v2
	v_mov_b32_e32 v9, v2
	v_mov_b32_e32 v10, v2
	v_mov_b32_e32 v11, v2
	v_mov_b32_e32 v12, v2
	v_mov_b32_e32 v13, v2
	v_mov_b64_e32 v[50:51], v[14:15]
	v_mov_b64_e32 v[48:49], v[12:13]
	v_mov_b64_e32 v[46:47], v[10:11]
	v_mov_b64_e32 v[44:45], v[8:9]
	v_mov_b64_e32 v[42:43], v[6:7]
	v_mov_b64_e32 v[40:41], v[4:5]
	v_mov_b64_e32 v[38:39], v[2:3]
	v_mov_b64_e32 v[36:37], v[0:1]
	v_lshl_add_u64 v[0:1], v[182:183], 0, s[36:37]
	s_add_i32 s61, s59, 0x4000
	s_mov_b32 s62, m0
	s_mov_b32 m0, s61
	s_nop 0
	global_load_lds_dwordx4 v[0:1], off
	s_mov_b32 m0, s62
	s_waitcnt vmcnt(3) lgkmcnt(0)
	s_barrier
	ds_read_b128 v[4:7], v191
	ds_read_b128 v[52:55], v191 offset:512
	v_lshl_add_u64 v[0:1], v[182:183], 0, s[76:77]
	s_add_i32 s61, s59, 0x8000
	s_cmp_gt_i32 s57, 3
	s_waitcnt vmcnt(3) lgkmcnt(1)
	v_mfma_f32_32x32x16_bf16 v[20:35], v[4:7], v[160:163], 0
	s_waitcnt lgkmcnt(0)
	v_mfma_f32_32x32x16_bf16 v[4:19], v[52:55], v[160:163], 0
	ds_read_b128 v[52:55], v191 offset:2048
	ds_read_b128 v[56:59], v191 offset:2560
	s_waitcnt vmcnt(2) lgkmcnt(1)
	v_mfma_f32_32x32x16_bf16 v[20:35], v[52:55], v[156:159], v[20:35]
	s_waitcnt lgkmcnt(0)
	v_mfma_f32_32x32x16_bf16 v[4:19], v[56:59], v[156:159], v[4:19]
	ds_read_b128 v[52:55], v191 offset:4096
	ds_read_b128 v[56:59], v191 offset:4608
	s_waitcnt vmcnt(1) lgkmcnt(1)
	v_mfma_f32_32x32x16_bf16 v[20:35], v[52:55], v[144:147], v[20:35]
	s_waitcnt lgkmcnt(0)
	v_mfma_f32_32x32x16_bf16 v[4:19], v[56:59], v[144:147], v[4:19]
	ds_read_b128 v[52:55], v191 offset:6144
	ds_read_b128 v[56:59], v191 offset:6656
	s_waitcnt vmcnt(0) lgkmcnt(1)
	v_mfma_f32_32x32x16_bf16 v[20:35], v[52:55], v[136:139], v[20:35]
	v_lshl_add_u64 v[52:53], v[180:181], 0, s[34:35]
	s_waitcnt lgkmcnt(0)
	v_mfma_f32_32x32x16_bf16 v[4:19], v[56:59], v[136:139], v[4:19]
	s_nop 15
	s_nop 7
	s_waitcnt vmcnt(0) lgkmcnt(0)
	s_barrier
	s_mov_b32 s62, m0
	s_mov_b32 m0, s59
	s_nop 0
	global_load_lds_dwordx4 v[0:1], off
	s_mov_b32 m0, s62
	s_nop 0
	s_mov_b32 s62, m0
	s_mov_b32 m0, s61
	s_nop 0
	global_load_lds_dwordx4 v[52:53], off
	s_mov_b32 m0, s62
	ds_read_b128 v[84:87], v191 offset:8192
	ds_read_b128 v[168:171], v191 offset:8704
	ds_read_b128 v[172:175], v191 offset:10240
	ds_read_b128 v[164:167], v191 offset:10752
	ds_read_b128 v[128:131], v191 offset:12288
	ds_read_b128 v[124:127], v191 offset:12800
	ds_read_b128 v[120:123], v191 offset:14336
	ds_read_b128 v[116:119], v191 offset:14848
	s_waitcnt vmcnt(2) lgkmcnt(0)
	s_barrier
	s_cbranch_scc0 .LBB0_730
	s_setprio 1

.LBB0_731:
	s_mov_b32 s44, s29
	s_mov_b32 s28, s25
	v_add_u32_e32 v195, s45, v190
	ds_read_b64_tr_b16 v[196:197], v195 offset:24576
	ds_read_b64_tr_b16 v[198:199], v195 offset:25088
	v_add_f32_e32 v88, v68, v69
	v_add_f32_e32 v88, v70, v88
	v_add_f32_e32 v88, v71, v88
	v_add_f32_e32 v88, v72, v88
	v_add_f32_e32 v88, v73, v88
	v_cvt_pk_bf16_f32 v152, v68, v69
	v_cvt_pk_bf16_f32 v153, v70, v71
	v_mfma_f32_32x32x16_bf16 v[100:115], v[84:87], v[160:163], 0
	ds_read_b64_tr_b16 v[68:69], v195 offset:28672
	ds_read_b64_tr_b16 v[70:71], v195 offset:29184
	v_add_f32_e32 v84, v74, v88
	v_add_f32_e32 v84, v75, v84
	v_add_f32_e32 v84, v76, v84
	v_add_f32_e32 v132, v77, v84
	v_mfma_f32_32x32x16_bf16 v[84:99], v[168:171], v[160:163], 0
	v_cvt_pk_bf16_f32 v154, v72, v73
	v_cvt_pk_bf16_f32 v155, v74, v75
	ds_read_b64_tr_b16 v[72:73], v195 offset:25600
	ds_read_b64_tr_b16 v[74:75], v195 offset:26112
	v_add_f32_e32 v132, v78, v132
	v_add_f32_e32 v132, v79, v132
	v_add_f32_e32 v132, v80, v132
	v_add_f32_e32 v132, v81, v132
	v_cvt_pk_bf16_f32 v148, v76, v77
	v_cvt_pk_bf16_f32 v149, v78, v79
	v_mfma_f32_32x32x16_bf16 v[100:115], v[172:175], v[156:159], v[100:115]
	ds_read_b64_tr_b16 v[76:77], v195 offset:29696
	ds_read_b64_tr_b16 v[78:79], v195 offset:30208
	v_mfma_f32_32x32x16_bf16 v[84:99], v[164:167], v[156:159], v[84:99]
	v_add_f32_e32 v132, v82, v132
	v_add_f32_e32 v132, v83, v132
	v_add_f32_e32 v132, v52, v132
	v_add_f32_e32 v132, v53, v132
	v_cvt_pk_bf16_f32 v150, v80, v81
	v_cvt_pk_bf16_f32 v151, v82, v83
	ds_read_b64_tr_b16 v[80:81], v195 offset:26624
	ds_read_b64_tr_b16 v[82:83], v195 offset:27136
	v_mfma_f32_32x32x16_bf16 v[100:115], v[128:131], v[144:147], v[100:115]
	v_add_f32_e32 v128, v54, v132
	v_add_f32_e32 v128, v55, v128
	v_add_f32_e32 v128, v56, v128
	v_add_f32_e32 v128, v57, v128
	v_cvt_pk_bf16_f32 v140, v52, v53
	v_cvt_pk_bf16_f32 v141, v54, v55
	ds_read_b64_tr_b16 v[52:53], v195 offset:30720
	ds_read_b64_tr_b16 v[54:55], v195 offset:31232
	v_mfma_f32_32x32x16_bf16 v[84:99], v[124:127], v[144:147], v[84:99]
	v_add_f32_e32 v124, v58, v128
	v_add_f32_e32 v124, v59, v124
	v_add_f32_e32 v124, v60, v124
	v_add_f32_e32 v124, v61, v124
	v_cvt_pk_bf16_f32 v142, v56, v57
	v_cvt_pk_bf16_f32 v143, v58, v59
	ds_read_b64_tr_b16 v[56:57], v195 offset:27648
	ds_read_b64_tr_b16 v[58:59], v195 offset:28160
	v_mfma_f32_32x32x16_bf16 v[100:115], v[120:123], v[136:139], v[100:115]
	v_add_f32_e32 v120, v62, v124
	v_add_f32_e32 v120, v63, v120
	v_add_f32_e32 v120, v64, v120
	v_add_f32_e32 v120, v65, v120
	v_cvt_pk_bf16_f32 v132, v60, v61
	v_cvt_pk_bf16_f32 v133, v62, v63
	ds_read_b64_tr_b16 v[60:61], v195 offset:31744
	ds_read_b64_tr_b16 v[62:63], v195 offset:32256
	v_mfma_f32_32x32x16_bf16 v[84:99], v[116:119], v[136:139], v[84:99]
	v_add_f32_e32 v116, v66, v120
	v_add_f32_e32 v195, v67, v116
	v_cvt_pk_bf16_f32 v134, v64, v65
	v_cvt_pk_bf16_f32 v135, v66, v67
	s_add_i32 m0, s25, s59
	v_lshl_add_u64 v[64:65], v[0:1], 0, s[76:77]
	global_load_lds_dwordx4 v[64:65], off
	s_add_i32 m0, s44, s58
	v_lshl_add_u64 v[64:65], v[184:185], 0, s[34:35]
	global_load_lds_dwordx4 v[64:65], off
	s_waitcnt lgkmcnt(14)
	v_mfma_f32_32x32x16_bf16 v[4:19], v[152:155], v[196:199], v[4:19]
	v_exp_f32_e32 v100, v100
	v_exp_f32_e32 v101, v101
	v_exp_f32_e32 v102, v102
	v_exp_f32_e32 v103, v103
	s_waitcnt lgkmcnt(12)
	v_mfma_f32_32x32x16_bf16 v[20:35], v[152:155], v[68:71], v[20:35]
	v_exp_f32_e32 v104, v104
	v_exp_f32_e32 v105, v105
	v_exp_f32_e32 v106, v106
	v_exp_f32_e32 v107, v107
	v_add_u32_e32 v68, s44, v191
	ds_read_b128 v[64:67], v68
	ds_read_b128 v[120:123], v68 offset:512
	s_waitcnt lgkmcnt(12)
	v_mfma_f32_32x32x16_bf16 v[4:19], v[148:151], v[72:75], v[4:19]
	v_exp_f32_e32 v108, v108
	v_exp_f32_e32 v109, v109
	v_exp_f32_e32 v110, v110
	v_exp_f32_e32 v111, v111
	ds_read_b128 v[124:127], v68 offset:2048
	ds_read_b128 v[128:131], v68 offset:2560
	s_waitcnt lgkmcnt(12)
	v_mfma_f32_32x32x16_bf16 v[20:35], v[148:151], v[76:79], v[20:35]
	v_exp_f32_e32 v112, v112
	v_exp_f32_e32 v113, v113
	v_exp_f32_e32 v114, v114
	v_exp_f32_e32 v115, v115
	ds_read_b128 v[164:167], v68 offset:4096
	ds_read_b128 v[168:171], v68 offset:4608
	s_waitcnt lgkmcnt(12)
	v_mfma_f32_32x32x16_bf16 v[4:19], v[140:143], v[80:83], v[4:19]
	v_exp_f32_e32 v84, v84
	v_exp_f32_e32 v85, v85
	v_exp_f32_e32 v86, v86
	v_exp_f32_e32 v87, v87
	ds_read_b128 v[172:175], v68 offset:6144
	ds_read_b128 v[116:119], v68 offset:6656
	s_waitcnt lgkmcnt(12)
	v_mfma_f32_32x32x16_bf16 v[20:35], v[140:143], v[52:55], v[20:35]
	v_exp_f32_e32 v88, v88
	v_exp_f32_e32 v89, v89
	v_exp_f32_e32 v90, v90
	v_exp_f32_e32 v91, v91
	s_waitcnt lgkmcnt(10)
	v_mfma_f32_32x32x16_bf16 v[4:19], v[132:135], v[56:59], v[4:19]
	v_exp_f32_e32 v92, v92
	v_exp_f32_e32 v93, v93
	v_exp_f32_e32 v94, v94
	v_exp_f32_e32 v95, v95
	s_waitcnt lgkmcnt(8)
	v_mfma_f32_32x32x16_bf16 v[20:35], v[132:135], v[60:63], v[20:35]
	v_exp_f32_e32 v96, v96
	v_exp_f32_e32 v97, v97
	v_exp_f32_e32 v98, v98
	v_exp_f32_e32 v99, v99
	s_waitcnt vmcnt(2) lgkmcnt(0)
	s_barrier
	s_add_i32 s25, s44, 0x2000
	s_cmpk_lg_i32 s44, 0x4000
	s_cselect_b32 s25, s25, 0
	v_add_u32_e32 v200, s28, v190
	ds_read_b64_tr_b16 v[196:197], v200 offset:24576
	ds_read_b64_tr_b16 v[198:199], v200 offset:25088
	v_mfma_f32_32x32x16_bf16 v[68:83], v[64:67], v[160:163], 0
	v_add_f32_e32 v52, v100, v101
	v_add_f32_e32 v52, v102, v52
	v_add_f32_e32 v52, v103, v52
	v_add_f32_e32 v52, v104, v52
	v_add_f32_e32 v52, v105, v52
	v_cvt_pk_bf16_f32 v152, v100, v101
	v_cvt_pk_bf16_f32 v153, v102, v103
	ds_read_b64_tr_b16 v[100:101], v200 offset:28672
	ds_read_b64_tr_b16 v[102:103], v200 offset:29184
	v_add_f32_e32 v52, v106, v52
	v_add_f32_e32 v52, v107, v52
	v_add_f32_e32 v52, v108, v52
	v_add_f32_e32 v132, v109, v52
	v_mfma_f32_32x32x16_bf16 v[52:67], v[120:123], v[160:163], 0
	v_cvt_pk_bf16_f32 v154, v104, v105
	v_cvt_pk_bf16_f32 v155, v106, v107
	ds_read_b64_tr_b16 v[104:105], v200 offset:25600
	ds_read_b64_tr_b16 v[106:107], v200 offset:26112
	v_mfma_f32_32x32x16_bf16 v[68:83], v[124:127], v[156:159], v[68:83]
	v_add_f32_e32 v120, v110, v132
	v_add_f32_e32 v120, v111, v120
	v_add_f32_e32 v120, v112, v120
	v_add_f32_e32 v120, v113, v120
	v_cvt_pk_bf16_f32 v148, v108, v109
	v_cvt_pk_bf16_f32 v149, v110, v111
	ds_read_b64_tr_b16 v[108:109], v200 offset:29696
	ds_read_b64_tr_b16 v[110:111], v200 offset:30208
	v_mfma_f32_32x32x16_bf16 v[52:67], v[128:131], v[156:159], v[52:67]
	v_add_f32_e32 v120, v114, v120
	v_add_f32_e32 v120, v115, v120
	v_add_f32_e32 v120, v84, v120
	v_add_f32_e32 v120, v85, v120
	v_cvt_pk_bf16_f32 v150, v112, v113
	v_cvt_pk_bf16_f32 v151, v114, v115
	ds_read_b64_tr_b16 v[112:113], v200 offset:26624
	ds_read_b64_tr_b16 v[114:115], v200 offset:27136
	v_mfma_f32_32x32x16_bf16 v[68:83], v[164:167], v[144:147], v[68:83]
	v_add_f32_e32 v120, v86, v120
	v_add_f32_e32 v120, v87, v120
	v_add_f32_e32 v120, v88, v120
	v_add_f32_e32 v120, v89, v120
	v_cvt_pk_bf16_f32 v140, v84, v85
	v_cvt_pk_bf16_f32 v141, v86, v87
	ds_read_b64_tr_b16 v[206:207], v200 offset:30720
	ds_read_b64_tr_b16 v[208:209], v200 offset:31232
	v_mfma_f32_32x32x16_bf16 v[52:67], v[168:171], v[144:147], v[52:67]
	v_add_f32_e32 v84, v90, v120
	v_add_f32_e32 v84, v91, v84
	v_add_f32_e32 v84, v92, v84
	v_add_f32_e32 v84, v93, v84
	v_cvt_pk_bf16_f32 v142, v88, v89
	v_cvt_pk_bf16_f32 v143, v90, v91
	ds_read_b64_tr_b16 v[88:89], v200 offset:27648
	ds_read_b64_tr_b16 v[90:91], v200 offset:28160
	v_mfma_f32_32x32x16_bf16 v[68:83], v[172:175], v[136:139], v[68:83]
	v_add_f32_e32 v84, v94, v84
	v_add_f32_e32 v84, v95, v84
	v_add_f32_e32 v84, v96, v84
	v_add_f32_e32 v84, v97, v84
	v_cvt_pk_bf16_f32 v132, v92, v93
	v_cvt_pk_bf16_f32 v133, v94, v95
	ds_read_b64_tr_b16 v[92:93], v200 offset:31744
	ds_read_b64_tr_b16 v[94:95], v200 offset:32256
	v_mfma_f32_32x32x16_bf16 v[52:67], v[116:119], v[136:139], v[52:67]
	v_add_f32_e32 v84, v98, v84
	v_add_f32_e32 v200, v99, v84
	v_cvt_pk_bf16_f32 v134, v96, v97
	v_cvt_pk_bf16_f32 v135, v98, v99
	s_mov_b64 s[28:29], 0x10000
	s_add_i32 m0, s44, s59
	v_lshl_add_u64 v[84:85], v[0:1], 0, s[28:29]
	global_load_lds_dwordx4 v[84:85], off
	s_add_i32 m0, s25, s58
	v_lshl_add_u64 v[184:185], v[184:185], 0, s[36:37]
	global_load_lds_dwordx4 v[184:185], off
	s_waitcnt lgkmcnt(14)
	v_mfma_f32_32x32x16_bf16 v[4:19], v[152:155], v[196:199], v[4:19]
	v_exp_f32_e32 v68, v68
	v_exp_f32_e32 v69, v69
	v_exp_f32_e32 v70, v70
	v_exp_f32_e32 v71, v71
	s_waitcnt lgkmcnt(12)
	v_mfma_f32_32x32x16_bf16 v[20:35], v[152:155], v[100:103], v[20:35]
	v_exp_f32_e32 v72, v72
	v_exp_f32_e32 v73, v73
	v_exp_f32_e32 v74, v74
	v_exp_f32_e32 v75, v75
	v_add_u32_e32 v96, s25, v191
	ds_read_b128 v[84:87], v96
	ds_read_b128 v[168:171], v96 offset:512
	s_waitcnt lgkmcnt(12)
	v_mfma_f32_32x32x16_bf16 v[4:19], v[148:151], v[104:107], v[4:19]
	v_exp_f32_e32 v76, v76
	v_exp_f32_e32 v77, v77
	v_exp_f32_e32 v78, v78
	v_exp_f32_e32 v79, v79
	ds_read_b128 v[172:175], v96 offset:2048
	ds_read_b128 v[164:167], v96 offset:2560
	s_waitcnt lgkmcnt(12)
	v_mfma_f32_32x32x16_bf16 v[20:35], v[148:151], v[108:111], v[20:35]
	v_exp_f32_e32 v80, v80
	v_exp_f32_e32 v81, v81
	v_exp_f32_e32 v82, v82
	v_exp_f32_e32 v83, v83
	ds_read_b128 v[128:131], v96 offset:4096
	ds_read_b128 v[124:127], v96 offset:4608
	s_waitcnt lgkmcnt(12)
	v_mfma_f32_32x32x16_bf16 v[4:19], v[140:143], v[112:115], v[4:19]
	v_exp_f32_e32 v52, v52
	v_exp_f32_e32 v53, v53
	v_exp_f32_e32 v54, v54
	v_exp_f32_e32 v55, v55
	ds_read_b128 v[120:123], v96 offset:6144
	ds_read_b128 v[116:119], v96 offset:6656
	s_waitcnt lgkmcnt(12)
	v_mfma_f32_32x32x16_bf16 v[20:35], v[140:143], v[206:209], v[20:35]
	v_exp_f32_e32 v56, v56
	v_exp_f32_e32 v57, v57
	v_exp_f32_e32 v58, v58
	v_exp_f32_e32 v59, v59
	s_waitcnt lgkmcnt(10)
	v_mfma_f32_32x32x16_bf16 v[4:19], v[132:135], v[88:91], v[4:19]
	v_exp_f32_e32 v60, v60
	v_exp_f32_e32 v61, v61
	v_exp_f32_e32 v62, v62
	v_exp_f32_e32 v63, v63
	s_waitcnt lgkmcnt(8)
	v_mfma_f32_32x32x16_bf16 v[20:35], v[132:135], v[92:95], v[20:35]
	v_exp_f32_e32 v64, v64
	v_exp_f32_e32 v65, v65
	v_exp_f32_e32 v66, v66
	v_exp_f32_e32 v67, v67
	s_add_i32 s28, s25, 0x2000
	s_waitcnt vmcnt(2) lgkmcnt(0)
	s_barrier
	s_cmpk_lg_i32 s25, 0x4000
	v_add_f32_e32 v88, v192, v195
	s_cselect_b32 s29, s28, 0
	s_add_i32 s24, s24, 2
	v_add_f32_e32 v192, v88, v200
	v_lshl_add_u64 v[0:1], v[0:1], 0, s[36:37]
	s_cmpk_gt_u32 s24, 0xf8
	s_mov_b32 s45, s44
	s_cbranch_scc0 .LBB0_731
	s_and_b32 s24, s60, 0x3fffffc0
	s_cmp_lg_u32 0, -1
	s_cselect_b32 s28, 0, 0
	s_addk_i32 s28, 0x6000
	s_lshl_b32 s24, s24, 2
	v_add3_u32 v0, v194, s28, v193
	s_add_i32 s28, s24, 0
	v_add_u32_e32 v1, s44, v190
	ds_read_b64_tr_b16 v[194:195], v1 offset:24576
	ds_read_b64_tr_b16 v[196:197], v1 offset:25088
	v_add_f32_e32 v88, v68, v69
	v_add_f32_e32 v88, v70, v88
	v_add_f32_e32 v88, v71, v88
	v_add_f32_e32 v88, v72, v88
	v_add_f32_e32 v88, v73, v88
	v_cvt_pk_bf16_f32 v152, v68, v69
	v_cvt_pk_bf16_f32 v153, v70, v71
	s_waitcnt lgkmcnt(9)
	v_mfma_f32_32x32x16_bf16 v[100:115], v[84:87], v[160:163], 0
	ds_read_b64_tr_b16 v[68:69], v1 offset:28672
	ds_read_b64_tr_b16 v[70:71], v1 offset:29184
	v_add_f32_e32 v84, v74, v88
	v_add_f32_e32 v84, v75, v84
	v_add_f32_e32 v84, v76, v84
	v_add_f32_e32 v132, v77, v84
	v_cvt_pk_bf16_f32 v154, v72, v73
	v_cvt_pk_bf16_f32 v155, v74, v75
	s_waitcnt lgkmcnt(10)
	v_mfma_f32_32x32x16_bf16 v[84:99], v[168:171], v[160:163], 0
	ds_read_b64_tr_b16 v[72:73], v1 offset:25600
	ds_read_b64_tr_b16 v[74:75], v1 offset:26112
	v_add_f32_e32 v132, v78, v132
	v_add_f32_e32 v132, v79, v132
	v_add_f32_e32 v132, v80, v132
	v_add_f32_e32 v132, v81, v132
	v_cvt_pk_bf16_f32 v148, v76, v77
	v_cvt_pk_bf16_f32 v149, v78, v79
	s_waitcnt lgkmcnt(11)
	v_mfma_f32_32x32x16_bf16 v[100:115], v[172:175], v[156:159], v[100:115]
	ds_read_b64_tr_b16 v[76:77], v1 offset:29696
	ds_read_b64_tr_b16 v[78:79], v1 offset:30208
	v_add_f32_e32 v132, v82, v132
	v_add_f32_e32 v132, v83, v132
	v_add_f32_e32 v132, v52, v132
	v_add_f32_e32 v132, v53, v132
	v_cvt_pk_bf16_f32 v150, v80, v81
	v_cvt_pk_bf16_f32 v151, v82, v83
	s_waitcnt lgkmcnt(12)
	v_mfma_f32_32x32x16_bf16 v[84:99], v[164:167], v[156:159], v[84:99]
	ds_read_b64_tr_b16 v[80:81], v1 offset:26624
	ds_read_b64_tr_b16 v[82:83], v1 offset:27136
	s_waitcnt lgkmcnt(13)
	v_mfma_f32_32x32x16_bf16 v[100:115], v[128:131], v[144:147], v[100:115]
	v_add_f32_e32 v128, v54, v132
	v_add_f32_e32 v128, v55, v128
	v_add_f32_e32 v128, v56, v128
	v_add_f32_e32 v128, v57, v128
	v_cvt_pk_bf16_f32 v140, v52, v53
	v_cvt_pk_bf16_f32 v141, v54, v55
	ds_read_b64_tr_b16 v[52:53], v1 offset:30720
	ds_read_b64_tr_b16 v[54:55], v1 offset:31232
	s_waitcnt lgkmcnt(14)
	v_mfma_f32_32x32x16_bf16 v[84:99], v[124:127], v[144:147], v[84:99]
	v_add_f32_e32 v124, v58, v128
	v_add_f32_e32 v124, v59, v124
	v_add_f32_e32 v124, v60, v124
	v_add_f32_e32 v124, v61, v124
	v_cvt_pk_bf16_f32 v142, v56, v57
	v_cvt_pk_bf16_f32 v143, v58, v59
	ds_read_b64_tr_b16 v[56:57], v1 offset:27648
	ds_read_b64_tr_b16 v[58:59], v1 offset:28160
	s_waitcnt lgkmcnt(14)
	v_mfma_f32_32x32x16_bf16 v[100:115], v[120:123], v[136:139], v[100:115]
	v_add_f32_e32 v120, v62, v124
	v_add_f32_e32 v120, v63, v120
	v_add_f32_e32 v120, v64, v120
	v_add_f32_e32 v120, v65, v120
	v_cvt_pk_bf16_f32 v132, v60, v61
	v_cvt_pk_bf16_f32 v133, v62, v63
	ds_read_b64_tr_b16 v[60:61], v1 offset:31744
	ds_read_b64_tr_b16 v[62:63], v1 offset:32256
	v_add_f32_e32 v1, v66, v120
	v_add_f32_e32 v1, v67, v1
	v_add_f32_e32 v1, 0, v1
	v_cvt_pk_bf16_f32 v134, v64, v65
	v_cvt_pk_bf16_f32 v135, v66, v67
	v_mfma_f32_32x32x16_bf16 v[84:99], v[116:119], v[136:139], v[84:99]
	s_mov_b64 s[46:47], 0x3f8000
	s_add_i32 s24, s25, s59
	v_lshl_add_u64 v[64:65], v[182:183], 0, s[46:47]
	s_mov_b32 s44, m0
	s_mov_b32 m0, s24
	s_nop 0
	global_load_lds_dwordx4 v[64:65], off
	s_mov_b32 m0, s44
	s_mov_b64 s[44:45], 0x3f0000
	v_lshl_add_u64 v[64:65], v[180:181], 0, s[44:45]
	s_add_i32 s24, s29, s58
	s_mov_b32 s44, m0
	s_mov_b32 m0, s24
	s_nop 0
	global_load_lds_dwordx4 v[64:65], off
	s_mov_b32 m0, s44
	v_add_f32_e32 v1, v192, v1
	s_waitcnt lgkmcnt(14)
	v_mfma_f32_32x32x16_bf16 v[4:19], v[152:155], v[194:197], v[4:19]
	v_exp_f32_e32 v100, v100
	v_exp_f32_e32 v101, v101
	v_exp_f32_e32 v102, v102
	v_exp_f32_e32 v103, v103
	s_waitcnt lgkmcnt(12)
	v_mfma_f32_32x32x16_bf16 v[20:35], v[152:155], v[68:71], v[20:35]
	v_exp_f32_e32 v104, v104
	v_exp_f32_e32 v105, v105
	v_exp_f32_e32 v106, v106
	v_exp_f32_e32 v107, v107
	v_add_u32_e32 v68, s29, v191
	ds_read_b128 v[64:67], v68
	ds_read_b128 v[164:167], v68 offset:512
	s_waitcnt lgkmcnt(12)
	v_mfma_f32_32x32x16_bf16 v[4:19], v[148:151], v[72:75], v[4:19]
	v_exp_f32_e32 v108, v108
	v_exp_f32_e32 v109, v109
	v_exp_f32_e32 v110, v110
	v_exp_f32_e32 v111, v111
	ds_read_b128 v[72:75], v68 offset:2048
	ds_read_b128 v[168:171], v68 offset:2560
	s_waitcnt lgkmcnt(12)
	v_mfma_f32_32x32x16_bf16 v[20:35], v[148:151], v[76:79], v[20:35]
	v_exp_f32_e32 v112, v112
	v_exp_f32_e32 v113, v113
	v_exp_f32_e32 v114, v114
	v_exp_f32_e32 v115, v115
	ds_read_b128 v[76:79], v68 offset:4096
	ds_read_b128 v[172:175], v68 offset:4608
	s_waitcnt lgkmcnt(12)
	v_mfma_f32_32x32x16_bf16 v[4:19], v[140:143], v[80:83], v[4:19]
	v_exp_f32_e32 v84, v84
	v_exp_f32_e32 v85, v85
	v_exp_f32_e32 v86, v86
	v_exp_f32_e32 v87, v87
	ds_read_b128 v[80:83], v68 offset:6144
	ds_read_b128 v[68:71], v68 offset:6656
	s_waitcnt lgkmcnt(12)
	v_mfma_f32_32x32x16_bf16 v[20:35], v[140:143], v[52:55], v[20:35]
	v_exp_f32_e32 v88, v88
	v_exp_f32_e32 v89, v89
	v_exp_f32_e32 v90, v90
	v_exp_f32_e32 v91, v91
	s_waitcnt lgkmcnt(10)
	v_mfma_f32_32x32x16_bf16 v[4:19], v[132:135], v[56:59], v[4:19]
	v_exp_f32_e32 v92, v92
	v_exp_f32_e32 v93, v93
	v_exp_f32_e32 v94, v94
	v_exp_f32_e32 v95, v95
	s_waitcnt lgkmcnt(8)
	v_mfma_f32_32x32x16_bf16 v[20:35], v[132:135], v[60:63], v[20:35]
	v_exp_f32_e32 v96, v96
	v_exp_f32_e32 v97, v97
	v_exp_f32_e32 v98, v98
	v_exp_f32_e32 v99, v99
	s_waitcnt vmcnt(2) lgkmcnt(0)
	s_barrier
	s_add_i32 s24, s29, 0x2000
	s_cmpk_lg_i32 s29, 0x4000
	s_cselect_b32 s44, s24, 0
	v_add_u32_e32 v184, s25, v190
	ds_read_b64_tr_b16 v[192:193], v184 offset:24576
	ds_read_b64_tr_b16 v[194:195], v184 offset:25088
	v_add_f32_e32 v52, v100, v101
	v_add_f32_e32 v52, v102, v52
	v_add_f32_e32 v52, v103, v52
	v_add_f32_e32 v52, v104, v52
	v_add_f32_e32 v52, v105, v52
	v_cvt_pk_bf16_f32 v152, v100, v101
	v_cvt_pk_bf16_f32 v153, v102, v103
	s_waitcnt lgkmcnt(9)
	v_mfma_f32_32x32x16_bf16 v[116:131], v[64:67], v[160:163], 0
	ds_read_b64_tr_b16 v[100:101], v184 offset:28672
	ds_read_b64_tr_b16 v[102:103], v184 offset:29184
	v_add_f32_e32 v52, v106, v52
	v_add_f32_e32 v52, v107, v52
	v_add_f32_e32 v52, v108, v52
	v_add_f32_e32 v132, v109, v52
	v_cvt_pk_bf16_f32 v154, v104, v105
	v_cvt_pk_bf16_f32 v155, v106, v107
	s_waitcnt lgkmcnt(10)
	v_mfma_f32_32x32x16_bf16 v[52:67], v[164:167], v[160:163], 0
	ds_read_b64_tr_b16 v[104:105], v184 offset:25600
	ds_read_b64_tr_b16 v[106:107], v184 offset:26112
	s_waitcnt lgkmcnt(11)
	v_mfma_f32_32x32x16_bf16 v[116:131], v[72:75], v[156:159], v[116:131]
	v_add_f32_e32 v72, v110, v132
	v_add_f32_e32 v72, v111, v72
	v_add_f32_e32 v72, v112, v72
	v_add_f32_e32 v132, v113, v72
	v_cvt_pk_bf16_f32 v148, v108, v109
	v_cvt_pk_bf16_f32 v149, v110, v111
	ds_read_b64_tr_b16 v[72:73], v184 offset:29696
	ds_read_b64_tr_b16 v[74:75], v184 offset:30208
	v_add_f32_e32 v108, v114, v132
	v_add_f32_e32 v108, v115, v108
	v_add_f32_e32 v108, v84, v108
	v_add_f32_e32 v132, v85, v108
	v_cvt_pk_bf16_f32 v150, v112, v113
	v_cvt_pk_bf16_f32 v151, v114, v115
	s_waitcnt lgkmcnt(12)
	v_mfma_f32_32x32x16_bf16 v[52:67], v[168:171], v[156:159], v[52:67]
	ds_read_b64_tr_b16 v[108:109], v184 offset:26624
	ds_read_b64_tr_b16 v[110:111], v184 offset:27136
	s_waitcnt lgkmcnt(13)
	v_mfma_f32_32x32x16_bf16 v[116:131], v[76:79], v[144:147], v[116:131]
	v_add_f32_e32 v76, v86, v132
	v_add_f32_e32 v76, v87, v76
	v_add_f32_e32 v76, v88, v76
	v_add_f32_e32 v112, v89, v76
	v_cvt_pk_bf16_f32 v140, v84, v85
	v_cvt_pk_bf16_f32 v141, v86, v87
	ds_read_b64_tr_b16 v[76:77], v184 offset:30720
	ds_read_b64_tr_b16 v[78:79], v184 offset:31232
	v_add_f32_e32 v84, v90, v112
	v_add_f32_e32 v84, v91, v84
	v_add_f32_e32 v84, v92, v84
	v_add_f32_e32 v84, v93, v84
	v_cvt_pk_bf16_f32 v142, v88, v89
	v_cvt_pk_bf16_f32 v143, v90, v91
	s_waitcnt lgkmcnt(14)
	v_mfma_f32_32x32x16_bf16 v[52:67], v[172:175], v[144:147], v[52:67]
	ds_read_b64_tr_b16 v[88:89], v184 offset:27648
	ds_read_b64_tr_b16 v[90:91], v184 offset:28160
	s_waitcnt lgkmcnt(14)
	v_mfma_f32_32x32x16_bf16 v[116:131], v[80:83], v[136:139], v[116:131]
	v_add_f32_e32 v80, v94, v84
	v_add_f32_e32 v80, v95, v80
	v_add_f32_e32 v80, v96, v80
	v_add_f32_e32 v84, v97, v80
	v_cvt_pk_bf16_f32 v132, v92, v93
	v_cvt_pk_bf16_f32 v133, v94, v95
	ds_read_b64_tr_b16 v[80:81], v184 offset:31744
	ds_read_b64_tr_b16 v[82:83], v184 offset:32256
	v_mfma_f32_32x32x16_bf16 v[52:67], v[68:71], v[136:139], v[52:67]
	v_add_f32_e32 v68, v98, v84
	v_add_f32_e32 v68, v99, v68
	v_add_f32_e32 v68, 0, v68
	v_cvt_pk_bf16_f32 v134, v96, v97
	v_cvt_pk_bf16_f32 v135, v98, v99
	s_mov_b64 s[60:61], 0x3fc000
	v_add_f32_e32 v1, v1, v68
	s_add_i32 s24, s29, s59
	v_lshl_add_u64 v[68:69], v[182:183], 0, s[60:61]
	s_mov_b32 s25, m0
	s_mov_b32 m0, s24
	s_nop 0
	global_load_lds_dwordx4 v[68:69], off
	s_mov_b32 m0, s25
	s_mov_b64 s[24:25], 0x3f4000
	s_add_i32 s45, s44, s58
	v_lshl_add_u64 v[68:69], v[180:181], 0, s[24:25]
	s_mov_b32 s24, m0
	s_mov_b32 m0, s45
	s_nop 0
	global_load_lds_dwordx4 v[68:69], off
	s_mov_b32 m0, s24
	s_waitcnt lgkmcnt(14)
	v_mfma_f32_32x32x16_bf16 v[4:19], v[152:155], v[192:195], v[4:19]
	v_exp_f32_e32 v116, v116
	v_exp_f32_e32 v117, v117
	v_exp_f32_e32 v118, v118
	v_exp_f32_e32 v119, v119
	s_waitcnt lgkmcnt(12)
	v_mfma_f32_32x32x16_bf16 v[20:35], v[152:155], v[100:103], v[20:35]
	v_exp_f32_e32 v120, v120
	v_exp_f32_e32 v121, v121
	v_exp_f32_e32 v122, v122
	v_exp_f32_e32 v123, v123
	v_add_u32_e32 v84, s44, v191
	ds_read_b128 v[68:71], v84
	ds_read_b128 v[92:95], v84 offset:512
	s_waitcnt lgkmcnt(12)
	v_mfma_f32_32x32x16_bf16 v[4:19], v[148:151], v[104:107], v[4:19]
	v_exp_f32_e32 v124, v124
	v_exp_f32_e32 v125, v125
	v_exp_f32_e32 v126, v126
	v_exp_f32_e32 v127, v127
	ds_read_b128 v[96:99], v84 offset:2048
	ds_read_b128 v[164:167], v84 offset:2560
	s_waitcnt lgkmcnt(12)
	v_mfma_f32_32x32x16_bf16 v[20:35], v[148:151], v[72:75], v[20:35]
	v_exp_f32_e32 v128, v128
	v_exp_f32_e32 v129, v129
	v_exp_f32_e32 v130, v130
	v_exp_f32_e32 v131, v131
	ds_read_b128 v[168:171], v84 offset:4096
	ds_read_b128 v[172:175], v84 offset:4608
	s_waitcnt lgkmcnt(12)
	v_mfma_f32_32x32x16_bf16 v[4:19], v[140:143], v[108:111], v[4:19]
	v_exp_f32_e32 v52, v52
	v_exp_f32_e32 v53, v53
	v_exp_f32_e32 v54, v54
	v_exp_f32_e32 v55, v55
	ds_read_b128 v[182:185], v84 offset:6144
	ds_read_b128 v[84:87], v84 offset:6656
	s_waitcnt lgkmcnt(12)
	v_mfma_f32_32x32x16_bf16 v[20:35], v[140:143], v[76:79], v[20:35]
	v_exp_f32_e32 v56, v56
	v_exp_f32_e32 v57, v57
	v_exp_f32_e32 v58, v58
	v_exp_f32_e32 v59, v59
	s_waitcnt lgkmcnt(10)
	v_mfma_f32_32x32x16_bf16 v[4:19], v[132:135], v[88:91], v[4:19]
	v_exp_f32_e32 v60, v60
	v_exp_f32_e32 v61, v61
	v_exp_f32_e32 v62, v62
	v_exp_f32_e32 v63, v63
	s_waitcnt lgkmcnt(8)
	v_mfma_f32_32x32x16_bf16 v[20:35], v[132:135], v[80:83], v[20:35]
	v_exp_f32_e32 v64, v64
	v_exp_f32_e32 v65, v65
	v_exp_f32_e32 v66, v66
	v_exp_f32_e32 v67, v67
	s_waitcnt vmcnt(2) lgkmcnt(0)
	s_barrier
	s_add_i32 s24, s44, 0x2000
	s_cmpk_lg_i32 s44, 0x4000
	s_cselect_b32 s25, s24, 0
	v_add_u32_e32 v192, s29, v190
	ds_read_b64_tr_b16 v[88:89], v192 offset:24576
	ds_read_b64_tr_b16 v[90:91], v192 offset:25088
	v_add_f32_e32 v72, v116, v117
	v_add_f32_e32 v72, v118, v72
	v_add_f32_e32 v72, v119, v72
	v_add_f32_e32 v72, v120, v72
	v_add_f32_e32 v72, v121, v72
	v_cvt_pk_bf16_f32 v152, v116, v117
	v_cvt_pk_bf16_f32 v153, v118, v119
	s_waitcnt lgkmcnt(9)
	v_mfma_f32_32x32x16_bf16 v[100:115], v[68:71], v[160:163], 0
	ds_read_b64_tr_b16 v[116:117], v192 offset:28672
	ds_read_b64_tr_b16 v[118:119], v192 offset:29184
	v_add_f32_e32 v68, v122, v72
	v_add_f32_e32 v68, v123, v68
	v_add_f32_e32 v68, v124, v68
	v_add_f32_e32 v132, v125, v68
	v_cvt_pk_bf16_f32 v154, v120, v121
	v_cvt_pk_bf16_f32 v155, v122, v123
	s_waitcnt lgkmcnt(10)
	v_mfma_f32_32x32x16_bf16 v[68:83], v[92:95], v[160:163], 0
	ds_read_b64_tr_b16 v[92:93], v192 offset:25600
	ds_read_b64_tr_b16 v[94:95], v192 offset:26112
	s_waitcnt lgkmcnt(11)
	v_mfma_f32_32x32x16_bf16 v[100:115], v[96:99], v[156:159], v[100:115]
	v_add_f32_e32 v96, v126, v132
	v_add_f32_e32 v96, v127, v96
	v_add_f32_e32 v96, v128, v96
	v_add_f32_e32 v120, v129, v96
	v_cvt_pk_bf16_f32 v148, v124, v125
	v_cvt_pk_bf16_f32 v149, v126, v127
	ds_read_b64_tr_b16 v[96:97], v192 offset:29696
	ds_read_b64_tr_b16 v[98:99], v192 offset:30208
	v_add_f32_e32 v120, v130, v120
	v_add_f32_e32 v120, v131, v120
	v_add_f32_e32 v120, v52, v120
	v_add_f32_e32 v124, v53, v120
	v_cvt_pk_bf16_f32 v150, v128, v129
	v_cvt_pk_bf16_f32 v151, v130, v131
	s_waitcnt lgkmcnt(12)
	v_mfma_f32_32x32x16_bf16 v[68:83], v[164:167], v[156:159], v[68:83]
	ds_read_b64_tr_b16 v[120:121], v192 offset:26624
	ds_read_b64_tr_b16 v[122:123], v192 offset:27136
	v_add_f32_e32 v124, v54, v124
	v_add_f32_e32 v124, v55, v124
	v_add_f32_e32 v124, v56, v124
	v_add_f32_e32 v124, v57, v124
	v_cvt_pk_bf16_f32 v140, v52, v53
	v_cvt_pk_bf16_f32 v141, v54, v55
	s_waitcnt lgkmcnt(13)
	v_mfma_f32_32x32x16_bf16 v[100:115], v[168:171], v[144:147], v[100:115]
	ds_read_b64_tr_b16 v[52:53], v192 offset:30720
	ds_read_b64_tr_b16 v[54:55], v192 offset:31232
	v_add_f32_e32 v124, v58, v124
	v_add_f32_e32 v124, v59, v124
	v_add_f32_e32 v124, v60, v124
	v_add_f32_e32 v124, v61, v124
	v_cvt_pk_bf16_f32 v142, v56, v57
	v_cvt_pk_bf16_f32 v143, v58, v59
	s_waitcnt lgkmcnt(14)
	v_mfma_f32_32x32x16_bf16 v[68:83], v[172:175], v[144:147], v[68:83]
	ds_read_b64_tr_b16 v[56:57], v192 offset:27648
	ds_read_b64_tr_b16 v[58:59], v192 offset:28160
	v_add_f32_e32 v124, v62, v124
	v_add_f32_e32 v124, v63, v124
	v_add_f32_e32 v124, v64, v124
	v_add_f32_e32 v124, v65, v124
	v_cvt_pk_bf16_f32 v132, v60, v61
	v_cvt_pk_bf16_f32 v133, v62, v63
	s_waitcnt lgkmcnt(14)
	v_mfma_f32_32x32x16_bf16 v[100:115], v[182:185], v[136:139], v[100:115]
	ds_read_b64_tr_b16 v[60:61], v192 offset:31744
	ds_read_b64_tr_b16 v[62:63], v192 offset:32256
	v_mfma_f32_32x32x16_bf16 v[68:83], v[84:87], v[136:139], v[68:83]
	v_add_f32_e32 v84, v66, v124
	v_add_f32_e32 v84, v67, v84
	v_add_f32_e32 v84, 0, v84
	v_cvt_pk_bf16_f32 v134, v64, v65
	v_cvt_pk_bf16_f32 v135, v66, v67
	v_lshl_add_u64 v[64:65], v[180:181], 0, s[46:47]
	s_add_i32 s24, s25, s58
	s_mov_b32 s29, m0
	s_mov_b32 m0, s24
	s_nop 0
	global_load_lds_dwordx4 v[64:65], off
	s_mov_b32 m0, s29
	v_add_f32_e32 v1, v1, v84
	s_waitcnt lgkmcnt(14)
	v_mfma_f32_32x32x16_bf16 v[4:19], v[152:155], v[88:91], v[4:19]
	v_exp_f32_e32 v100, v100
	v_exp_f32_e32 v101, v101
	v_exp_f32_e32 v102, v102
	v_exp_f32_e32 v103, v103
	s_waitcnt lgkmcnt(12)
	v_mfma_f32_32x32x16_bf16 v[20:35], v[152:155], v[116:119], v[20:35]
	v_exp_f32_e32 v104, v104
	v_exp_f32_e32 v105, v105
	v_exp_f32_e32 v106, v106
	v_exp_f32_e32 v107, v107
	v_add_u32_e32 v84, s25, v191
	ds_read_b128 v[64:67], v84
	ds_read_b128 v[124:127], v84 offset:512
	s_waitcnt lgkmcnt(12)
	v_mfma_f32_32x32x16_bf16 v[4:19], v[148:151], v[92:95], v[4:19]
	v_exp_f32_e32 v108, v108
	v_exp_f32_e32 v109, v109
	v_exp_f32_e32 v110, v110
	v_exp_f32_e32 v111, v111
	ds_read_b128 v[128:131], v84 offset:2048
	ds_read_b128 v[164:167], v84 offset:2560
	s_waitcnt lgkmcnt(12)
	v_mfma_f32_32x32x16_bf16 v[20:35], v[148:151], v[96:99], v[20:35]
	v_exp_f32_e32 v112, v112
	v_exp_f32_e32 v113, v113
	v_exp_f32_e32 v114, v114
	v_exp_f32_e32 v115, v115
	ds_read_b128 v[168:171], v84 offset:4096
	ds_read_b128 v[172:175], v84 offset:4608
	s_waitcnt lgkmcnt(12)
	v_mfma_f32_32x32x16_bf16 v[4:19], v[140:143], v[120:123], v[4:19]
	v_exp_f32_e32 v68, v68
	v_exp_f32_e32 v69, v69
	v_exp_f32_e32 v70, v70
	v_exp_f32_e32 v71, v71
	ds_read_b128 v[120:123], v84 offset:6144
	ds_read_b128 v[116:119], v84 offset:6656
	s_waitcnt lgkmcnt(12)
	v_mfma_f32_32x32x16_bf16 v[20:35], v[140:143], v[52:55], v[20:35]
	v_exp_f32_e32 v72, v72
	v_exp_f32_e32 v73, v73
	v_exp_f32_e32 v74, v74
	v_exp_f32_e32 v75, v75
	s_waitcnt lgkmcnt(10)
	v_mfma_f32_32x32x16_bf16 v[4:19], v[132:135], v[56:59], v[4:19]
	v_exp_f32_e32 v76, v76
	v_exp_f32_e32 v77, v77
	v_exp_f32_e32 v78, v78
	v_exp_f32_e32 v79, v79
	s_waitcnt lgkmcnt(8)
	v_mfma_f32_32x32x16_bf16 v[20:35], v[132:135], v[60:63], v[20:35]
	v_exp_f32_e32 v80, v80
	v_exp_f32_e32 v81, v81
	v_exp_f32_e32 v82, v82
	v_exp_f32_e32 v83, v83
	s_waitcnt vmcnt(1) lgkmcnt(0)
	s_barrier
	s_add_i32 s24, s25, 0x2000
	s_cmpk_lg_i32 s25, 0x4000
	s_cselect_b32 s24, s24, 0
	v_add_u32_e32 v192, s44, v190
	ds_read_b64_tr_b16 v[182:183], v192 offset:24576
	ds_read_b64_tr_b16 v[184:185], v192 offset:25088
	v_add_f32_e32 v52, v100, v101
	v_add_f32_e32 v52, v102, v52
	v_add_f32_e32 v52, v103, v52
	v_add_f32_e32 v52, v104, v52
	v_add_f32_e32 v52, v105, v52
	v_cvt_pk_bf16_f32 v152, v100, v101
	v_cvt_pk_bf16_f32 v153, v102, v103
	s_waitcnt lgkmcnt(9)
	v_mfma_f32_32x32x16_bf16 v[84:99], v[64:67], v[160:163], 0
	ds_read_b64_tr_b16 v[100:101], v192 offset:28672
	ds_read_b64_tr_b16 v[102:103], v192 offset:29184
	v_add_f32_e32 v52, v106, v52
	v_add_f32_e32 v52, v107, v52
	v_add_f32_e32 v52, v108, v52
	v_add_f32_e32 v132, v109, v52
	v_cvt_pk_bf16_f32 v154, v104, v105
	v_cvt_pk_bf16_f32 v155, v106, v107
	s_waitcnt lgkmcnt(10)
	v_mfma_f32_32x32x16_bf16 v[52:67], v[124:127], v[160:163], 0
	ds_read_b64_tr_b16 v[104:105], v192 offset:25600
	ds_read_b64_tr_b16 v[106:107], v192 offset:26112
	v_add_f32_e32 v124, v110, v132
	v_add_f32_e32 v124, v111, v124
	v_add_f32_e32 v124, v112, v124
	v_add_f32_e32 v124, v113, v124
	v_cvt_pk_bf16_f32 v148, v108, v109
	v_cvt_pk_bf16_f32 v149, v110, v111
	s_waitcnt lgkmcnt(11)
	v_mfma_f32_32x32x16_bf16 v[84:99], v[128:131], v[156:159], v[84:99]
	ds_read_b64_tr_b16 v[108:109], v192 offset:29696
	ds_read_b64_tr_b16 v[110:111], v192 offset:30208
	v_add_f32_e32 v124, v114, v124
	v_add_f32_e32 v124, v115, v124
	v_add_f32_e32 v124, v68, v124
	v_add_f32_e32 v124, v69, v124
	v_cvt_pk_bf16_f32 v150, v112, v113
	v_cvt_pk_bf16_f32 v151, v114, v115
	s_waitcnt lgkmcnt(12)
	v_mfma_f32_32x32x16_bf16 v[52:67], v[164:167], v[156:159], v[52:67]
	ds_read_b64_tr_b16 v[112:113], v192 offset:26624
	ds_read_b64_tr_b16 v[114:115], v192 offset:27136
	v_add_f32_e32 v124, v70, v124
	v_add_f32_e32 v124, v71, v124
	v_add_f32_e32 v124, v72, v124
	v_add_f32_e32 v124, v73, v124
	v_cvt_pk_bf16_f32 v140, v68, v69
	v_cvt_pk_bf16_f32 v141, v70, v71
	s_waitcnt lgkmcnt(13)
	v_mfma_f32_32x32x16_bf16 v[84:99], v[168:171], v[144:147], v[84:99]
	ds_read_b64_tr_b16 v[68:69], v192 offset:30720
	ds_read_b64_tr_b16 v[70:71], v192 offset:31232
	v_add_f32_e32 v124, v74, v124
	v_add_f32_e32 v124, v75, v124
	v_add_f32_e32 v124, v76, v124
	v_add_f32_e32 v124, v77, v124
	v_cvt_pk_bf16_f32 v142, v72, v73
	v_cvt_pk_bf16_f32 v143, v74, v75
	s_waitcnt lgkmcnt(14)
	v_mfma_f32_32x32x16_bf16 v[52:67], v[172:175], v[144:147], v[52:67]
	ds_read_b64_tr_b16 v[72:73], v192 offset:27648
	ds_read_b64_tr_b16 v[74:75], v192 offset:28160
	s_waitcnt lgkmcnt(14)
	v_mfma_f32_32x32x16_bf16 v[84:99], v[120:123], v[136:139], v[84:99]
	v_add_f32_e32 v120, v78, v124
	v_add_f32_e32 v120, v79, v120
	v_add_f32_e32 v120, v80, v120
	v_add_f32_e32 v120, v81, v120
	v_cvt_pk_bf16_f32 v132, v76, v77
	v_cvt_pk_bf16_f32 v133, v78, v79
	ds_read_b64_tr_b16 v[76:77], v192 offset:31744
	ds_read_b64_tr_b16 v[78:79], v192 offset:32256
	v_mfma_f32_32x32x16_bf16 v[52:67], v[116:119], v[136:139], v[52:67]
	v_add_f32_e32 v116, v82, v120
	v_add_f32_e32 v116, v83, v116
	v_add_f32_e32 v116, 0, v116
	v_cvt_pk_bf16_f32 v134, v80, v81
	v_cvt_pk_bf16_f32 v135, v82, v83
	s_add_i32 s29, s24, s58
	v_lshl_add_u64 v[80:81], v[180:181], 0, s[60:61]
	s_mov_b32 s44, m0
	s_mov_b32 m0, s29
	s_nop 0
	global_load_lds_dwordx4 v[80:81], off
	s_mov_b32 m0, s44
	v_add_f32_e32 v1, v1, v116
	s_waitcnt lgkmcnt(14)
	v_mfma_f32_32x32x16_bf16 v[4:19], v[152:155], v[182:185], v[4:19]
	v_exp_f32_e32 v84, v84
	v_exp_f32_e32 v85, v85
	v_exp_f32_e32 v86, v86
	v_exp_f32_e32 v87, v87
	s_waitcnt lgkmcnt(12)
	v_mfma_f32_32x32x16_bf16 v[20:35], v[152:155], v[100:103], v[20:35]
	v_exp_f32_e32 v88, v88
	v_exp_f32_e32 v89, v89
	v_exp_f32_e32 v90, v90
	v_exp_f32_e32 v91, v91
	v_add_u32_e32 v80, s24, v191
	ds_read_b128 v[116:119], v80
	ds_read_b128 v[120:123], v80 offset:512
	s_waitcnt lgkmcnt(12)
	v_mfma_f32_32x32x16_bf16 v[4:19], v[148:151], v[104:107], v[4:19]
	v_exp_f32_e32 v92, v92
	v_exp_f32_e32 v93, v93
	v_exp_f32_e32 v94, v94
	v_exp_f32_e32 v95, v95
	ds_read_b128 v[104:107], v80 offset:2048
	ds_read_b128 v[124:127], v80 offset:2560
	s_waitcnt lgkmcnt(12)
	v_mfma_f32_32x32x16_bf16 v[20:35], v[148:151], v[108:111], v[20:35]
	v_exp_f32_e32 v96, v96
	v_exp_f32_e32 v97, v97
	v_exp_f32_e32 v98, v98
	v_exp_f32_e32 v99, v99
	ds_read_b128 v[108:111], v80 offset:4096
	ds_read_b128 v[128:131], v80 offset:4608
	s_waitcnt lgkmcnt(12)
	v_mfma_f32_32x32x16_bf16 v[4:19], v[140:143], v[112:115], v[4:19]
	v_exp_f32_e32 v52, v52
	v_exp_f32_e32 v53, v53
	v_exp_f32_e32 v54, v54
	v_exp_f32_e32 v55, v55
	ds_read_b128 v[112:115], v80 offset:6144
	ds_read_b128 v[100:103], v80 offset:6656
	s_waitcnt lgkmcnt(12)
	v_mfma_f32_32x32x16_bf16 v[20:35], v[140:143], v[68:71], v[20:35]
	v_exp_f32_e32 v56, v56
	v_exp_f32_e32 v57, v57
	v_exp_f32_e32 v58, v58
	v_exp_f32_e32 v59, v59
	s_waitcnt lgkmcnt(10)
	v_mfma_f32_32x32x16_bf16 v[4:19], v[132:135], v[72:75], v[4:19]
	v_exp_f32_e32 v60, v60
	v_exp_f32_e32 v61, v61
	v_exp_f32_e32 v62, v62
	v_exp_f32_e32 v63, v63
	s_waitcnt lgkmcnt(8)
	v_mfma_f32_32x32x16_bf16 v[20:35], v[132:135], v[76:79], v[20:35]
	v_exp_f32_e32 v64, v64
	v_exp_f32_e32 v65, v65
	v_exp_f32_e32 v66, v66
	v_exp_f32_e32 v67, v67
	s_waitcnt vmcnt(0) lgkmcnt(0)
	s_barrier
	v_add_u32_e32 v168, s25, v190
	ds_read_b64_tr_b16 v[164:165], v168 offset:24576
	ds_read_b64_tr_b16 v[166:167], v168 offset:25088
	v_add_f32_e32 v68, v84, v85
	v_add_f32_e32 v68, v86, v68
	v_add_f32_e32 v68, v87, v68
	v_add_f32_e32 v68, v88, v68
	v_add_f32_e32 v132, v89, v68
	v_cvt_pk_bf16_f32 v152, v84, v85
	v_cvt_pk_bf16_f32 v153, v86, v87
	s_waitcnt lgkmcnt(9)
	v_mfma_f32_32x32x16_bf16 v[68:83], v[116:119], v[160:163], 0
	ds_read_b64_tr_b16 v[84:85], v168 offset:28672
	ds_read_b64_tr_b16 v[86:87], v168 offset:29184
	v_add_f32_e32 v116, v90, v132
	v_add_f32_e32 v116, v91, v116
	v_add_f32_e32 v116, v92, v116
	v_add_f32_e32 v116, v93, v116
	v_cvt_pk_bf16_f32 v154, v88, v89
	v_cvt_pk_bf16_f32 v155, v90, v91
	s_waitcnt lgkmcnt(10)
	v_mfma_f32_32x32x16_bf16 v[36:51], v[120:123], v[160:163], 0
	ds_read_b64_tr_b16 v[88:89], v168 offset:25600
	ds_read_b64_tr_b16 v[90:91], v168 offset:26112
	s_waitcnt lgkmcnt(11)
	v_mfma_f32_32x32x16_bf16 v[68:83], v[104:107], v[156:159], v[68:83]
	v_add_f32_e32 v104, v94, v116
	v_add_f32_e32 v104, v95, v104
	v_add_f32_e32 v104, v96, v104
	v_add_f32_e32 v104, v97, v104
	v_cvt_pk_bf16_f32 v148, v92, v93
	v_cvt_pk_bf16_f32 v149, v94, v95
	ds_read_b64_tr_b16 v[92:93], v168 offset:29696
	ds_read_b64_tr_b16 v[94:95], v168 offset:30208
	v_add_f32_e32 v104, v98, v104
	v_add_f32_e32 v104, v99, v104
	v_add_f32_e32 v104, v52, v104
	v_add_f32_e32 v104, v53, v104
	v_cvt_pk_bf16_f32 v150, v96, v97
	v_cvt_pk_bf16_f32 v151, v98, v99
	s_waitcnt lgkmcnt(12)
	v_mfma_f32_32x32x16_bf16 v[36:51], v[124:127], v[156:159], v[36:51]
	ds_read_b64_tr_b16 v[96:97], v168 offset:26624
	ds_read_b64_tr_b16 v[98:99], v168 offset:27136
	v_add_f32_e32 v104, v54, v104
	v_add_f32_e32 v104, v55, v104
	v_add_f32_e32 v104, v56, v104
	v_add_f32_e32 v104, v57, v104
	v_cvt_pk_bf16_f32 v140, v52, v53
	v_cvt_pk_bf16_f32 v141, v54, v55
	s_waitcnt lgkmcnt(13)
	v_mfma_f32_32x32x16_bf16 v[68:83], v[108:111], v[144:147], v[68:83]
	ds_read_b64_tr_b16 v[52:53], v168 offset:30720
	ds_read_b64_tr_b16 v[54:55], v168 offset:31232
	v_add_f32_e32 v104, v58, v104
	v_add_f32_e32 v104, v59, v104
	v_add_f32_e32 v104, v60, v104
	v_add_f32_e32 v104, v61, v104
	v_cvt_pk_bf16_f32 v142, v56, v57
	v_cvt_pk_bf16_f32 v143, v58, v59
	s_waitcnt lgkmcnt(14)
	v_mfma_f32_32x32x16_bf16 v[36:51], v[128:131], v[144:147], v[36:51]
	ds_read_b64_tr_b16 v[56:57], v168 offset:27648
	ds_read_b64_tr_b16 v[58:59], v168 offset:28160
	v_add_f32_e32 v104, v62, v104
	v_add_f32_e32 v104, v63, v104
	v_add_f32_e32 v104, v64, v104
	v_add_f32_e32 v104, v65, v104
	v_cvt_pk_bf16_f32 v132, v60, v61
	v_cvt_pk_bf16_f32 v133, v62, v63
	s_waitcnt lgkmcnt(14)
	v_mfma_f32_32x32x16_bf16 v[68:83], v[112:115], v[136:139], v[68:83]
	ds_read_b64_tr_b16 v[60:61], v168 offset:31744
	ds_read_b64_tr_b16 v[62:63], v168 offset:32256
	v_mfma_f32_32x32x16_bf16 v[36:51], v[100:103], v[136:139], v[36:51]
	v_add_f32_e32 v100, v66, v104
	v_add_f32_e32 v100, v67, v100
	v_add_f32_e32 v100, 0, v100
	v_cvt_pk_bf16_f32 v134, v64, v65
	v_cvt_pk_bf16_f32 v135, v66, v67
	s_waitcnt lgkmcnt(14)
	v_mfma_f32_32x32x16_bf16 v[4:19], v[152:155], v[164:167], v[4:19]
	s_nop 1
	v_exp_f32_e32 v68, v68
	v_exp_f32_e32 v69, v69
	v_exp_f32_e32 v70, v70
	v_exp_f32_e32 v71, v71
	s_waitcnt lgkmcnt(12)
	v_mfma_f32_32x32x16_bf16 v[20:35], v[152:155], v[84:87], v[20:35]
	v_exp_f32_e32 v72, v72
	v_exp_f32_e32 v73, v73
	v_exp_f32_e32 v74, v74
	v_exp_f32_e32 v75, v75
	s_waitcnt lgkmcnt(10)
	v_mfma_f32_32x32x16_bf16 v[4:19], v[148:151], v[88:91], v[4:19]
	v_exp_f32_e32 v76, v76
	v_exp_f32_e32 v77, v77
	v_exp_f32_e32 v78, v78
	v_exp_f32_e32 v79, v79
	s_waitcnt lgkmcnt(8)
	v_mfma_f32_32x32x16_bf16 v[20:35], v[148:151], v[92:95], v[20:35]
	v_exp_f32_e32 v80, v80
	v_exp_f32_e32 v81, v81
	v_exp_f32_e32 v82, v82
	v_exp_f32_e32 v83, v83
	s_waitcnt lgkmcnt(6)
	v_mfma_f32_32x32x16_bf16 v[4:19], v[140:143], v[96:99], v[4:19]
	v_exp_f32_e32 v36, v36
	v_exp_f32_e32 v37, v37
	v_exp_f32_e32 v38, v38
	v_exp_f32_e32 v39, v39
	s_waitcnt lgkmcnt(4)
	v_mfma_f32_32x32x16_bf16 v[20:35], v[140:143], v[52:55], v[20:35]
	v_exp_f32_e32 v40, v40
	v_exp_f32_e32 v41, v41
	v_exp_f32_e32 v42, v42
	v_exp_f32_e32 v43, v43
	s_waitcnt lgkmcnt(2)
	v_mfma_f32_32x32x16_bf16 v[4:19], v[132:135], v[56:59], v[4:19]
	v_exp_f32_e32 v44, v44
	v_exp_f32_e32 v45, v45
	v_exp_f32_e32 v46, v46
	v_exp_f32_e32 v47, v47
	s_waitcnt lgkmcnt(0)
	v_mfma_f32_32x32x16_bf16 v[20:35], v[132:135], v[60:63], v[20:35]
	v_exp_f32_e32 v48, v48
	v_exp_f32_e32 v49, v49
	v_exp_f32_e32 v50, v50
	v_exp_f32_e32 v51, v51
	v_add_f32_e32 v52, v68, v69
	v_add_f32_e32 v52, v70, v52
	v_add_f32_e32 v52, v71, v52
	v_add_f32_e32 v52, v72, v52
	v_add_f32_e32 v52, v73, v52
	v_add_f32_e32 v52, v74, v52
	v_add_f32_e32 v52, v75, v52
	v_add_f32_e32 v52, v76, v52
	v_add_f32_e32 v52, v77, v52
	v_add_f32_e32 v52, v78, v52
	v_add_f32_e32 v52, v79, v52
	v_add_f32_e32 v52, v80, v52
	v_add_f32_e32 v52, v81, v52
	v_add_f32_e32 v52, v82, v52
	v_add_f32_e32 v52, v83, v52
	v_add_f32_e32 v52, v36, v52
	v_add_f32_e32 v52, v37, v52
	v_add_f32_e32 v52, v38, v52
	v_add_f32_e32 v52, v39, v52
	v_add_f32_e32 v52, v40, v52
	v_add_f32_e32 v52, v41, v52
	v_add_f32_e32 v52, v42, v52
	v_add_f32_e32 v52, v43, v52
	v_add_f32_e32 v52, v44, v52
	v_add_f32_e32 v52, v45, v52
	v_add_f32_e32 v52, v46, v52
	v_add_f32_e32 v52, v47, v52
	v_add_f32_e32 v52, v48, v52
	v_add_f32_e32 v52, v49, v52
	v_add_f32_e32 v52, v50, v52
	v_add_f32_e32 v52, v51, v52
	v_add_f32_e32 v1, v1, v100
	v_add_f32_e32 v1, v1, v52
	v_cvt_pk_bf16_f32 v52, v68, v69
	v_cvt_pk_bf16_f32 v53, v70, v71
	v_cvt_pk_bf16_f32 v54, v72, v73
	v_cvt_pk_bf16_f32 v55, v74, v75
	v_cvt_pk_bf16_f32 v56, v76, v77
	v_cvt_pk_bf16_f32 v57, v78, v79
	v_cvt_pk_bf16_f32 v58, v80, v81
	v_cvt_pk_bf16_f32 v59, v82, v83
	v_cvt_pk_bf16_f32 v36, v36, v37
	v_cvt_pk_bf16_f32 v37, v38, v39
	v_cvt_pk_bf16_f32 v38, v40, v41
	v_cvt_pk_bf16_f32 v39, v42, v43
	v_cvt_pk_bf16_f32 v40, v44, v45
	v_cvt_pk_bf16_f32 v41, v46, v47
	v_cvt_pk_bf16_f32 v42, v48, v49
	v_cvt_pk_bf16_f32 v43, v50, v51
	v_add3_u32 v0, v0, v3, s24
	ds_read_b64_tr_b16 v[44:45],v0 offset:0
	ds_read_b64_tr_b16 v[46:47],v0 offset:512
	ds_read_b64_tr_b16 v[48:49],v0 offset:1024
	ds_read_b64_tr_b16 v[50:51],v0 offset:1536
	ds_read_b64_tr_b16 v[60:61],v0 offset:2048
	ds_read_b64_tr_b16 v[62:63],v0 offset:2560
	ds_read_b64_tr_b16 v[64:65],v0 offset:3072
	ds_read_b64_tr_b16 v[66:67],v0 offset:3584
	s_waitcnt lgkmcnt(0)
	s_nop 0
	v_mfma_f32_32x32x16_bf16 v[4:19], v[52:55], v[44:47], v[4:19]
	ds_read_b64_tr_b16 v[44:45],v0 offset:4096
	ds_read_b64_tr_b16 v[46:47],v0 offset:4608
	v_mfma_f32_32x32x16_bf16 v[4:19], v[56:59], v[48:51], v[4:19]
	ds_read_b64_tr_b16 v[48:49],v0 offset:5120
	ds_read_b64_tr_b16 v[50:51],v0 offset:5632
	v_mfma_f32_32x32x16_bf16 v[4:19], v[36:39], v[60:63], v[4:19]
	ds_read_b64_tr_b16 v[60:61],v0 offset:6144
	ds_read_b64_tr_b16 v[62:63],v0 offset:6656
	v_mfma_f32_32x32x16_bf16 v[4:19], v[40:43], v[64:67], v[4:19]
	ds_read_b64_tr_b16 v[64:65],v0 offset:7168
	ds_read_b64_tr_b16 v[66:67],v0 offset:7680
	s_waitcnt lgkmcnt(0)
	v_mfma_f32_32x32x16_bf16 v[20:35], v[52:55], v[44:47], v[20:35]
	v_mfma_f32_32x32x16_bf16 v[20:35], v[56:59], v[48:51], v[20:35]
	v_mfma_f32_32x32x16_bf16 v[20:35], v[36:39], v[60:63], v[20:35]
	v_mfma_f32_32x32x16_bf16 v[20:35], v[40:43], v[64:67], v[20:35]
	s_setprio 0
	v_mov_b32_e32 v0, v1
	s_nop 1
	v_permlane32_swap_b32_e32 v1, v0
	v_cmp_gt_u32_e32 vcc, 32, v186
	s_and_saveexec_b64 s[24:25], vcc
	s_cbranch_execz .LBB0_727
	v_lshl_add_u32 v3, v188, 2, s28
	v_add_f32_e32 v0, v1, v0
	ds_write_b32 v3, v0 offset:49280
	s_branch .LBB0_727
